# in-proj tile index permuted (bit 4 of j moved to bit 5) so the last partial round runs on workgroups whose CU-mates are idle
# speedup vs baseline: 1.0018x; 1.0018x over previous
.LBB0_1288:
	s_andn2_b64 vcc, exec, s[10:11]
	s_cbranch_vccnz .LBB0_2295
	v_readlane_b32 s8, v246, 21
	v_readlane_b32 s9, v246, 22
	s_and_b64 s[8:9], s[8:9], exec
	s_cselect_b32 s2, 18, 25
	s_mul_i32 s1, s2, 12
	s_cmp_ge_u32 s83, s1
	s_mov_b64 s[48:49], s[84:85]
	s_cbranch_scc1 .LBB0_2295
	v_readlane_b32 s8, v246, 21
	v_readlane_b32 s9, v246, 22
	s_and_b64 s[8:9], s[8:9], exec
	s_load_dwordx2 s[8:9], s[48:49], 0x108
	s_mov_b32 s11, 0x10078100
	s_mov_b32 s6, 0x480000
	s_cselect_b32 s11, s11, 0x10f98100
	s_cselect_b32 s6, s6, 0x640000
	s_waitcnt lgkmcnt(0)
	s_add_u32 s11, s8, s11
	s_mul_hi_i32 s10, s6, s0
	s_mul_i32 s6, s6, s0
	s_addc_u32 s12, s9, 0
	s_add_u32 s50, s11, s6
	s_addc_u32 s51, s12, s10
	s_lshl_b32 s2, s2, 2
	s_lshl_b32 s18, s0, 8
	s_add_u32 s52, s8, 0x14958100
	s_addc_u32 s53, s9, 0
	s_add_u32 s54, s8, 0x17358100
	s_addc_u32 s55, s9, 0
	s_add_u32 s56, s8, 0x16d58100
	s_addc_u32 s57, s9, 0
	s_add_u32 s58, s8, 0x19158100
	s_addc_u32 s59, s9, 0
	s_add_u32 s60, s8, 0x17958100
	s_addc_u32 s61, s9, 0
	s_add_u32 s62, s8, 0x16758100
	s_addc_u32 s63, s9, 0
	s_add_u32 s64, s8, 0x16158100
	s_addc_u32 s65, s9, 0
	s_add_u32 s66, s8, 0x1a958100
	s_addc_u32 s67, s9, 0
	v_cvt_f32_u32_e32 v0, s2
	s_add_u32 s68, s8, 0x1aa58100
	s_addc_u32 s69, s9, 0
	s_add_u32 s70, s8, 0x14818100
	s_addc_u32 s71, s9, 0
	v_rcp_iflag_f32_e32 v0, v0
	s_add_u32 s72, s8, 0x1ae98100
	s_addc_u32 s73, s9, 0
	s_add_u32 s74, s8, 0x1aa98100
	s_addc_u32 s75, s9, 0
	v_mul_f32_e32 v0, 0x4f7ffffe, v0
	s_add_u32 s76, s8, 0x18258100
	v_cvt_u32_f32_e32 v0, v0
	s_addc_u32 s77, s9, 0
	s_add_u32 s78, s8, 0x12018100
	s_addc_u32 s79, s9, 0
	s_sub_i32 s19, 0, s2
	s_waitcnt vmcnt(0)
	v_mul_lo_u32 v2, s19, v0
	v_mul_hi_u32 v2, v0, v2
	v_add_u32_e32 v166, v0, v2
	s_and_b32 s20, s83, 15
	s_lshr_b32 s6, s83, 5
	s_lshl_b32 s6, s6, 4
	s_or_b32 s20, s20, s6
	s_bfe_u32 s6, s83, 0x10004
	s_lshl_b32 s6, s6, 5
	s_or_b32 s20, s20, s6
	s_mov_b32 s12, 0x10000
	s_mov_b32 s21, 0x30000
	s_mov_b32 s23, 0x20000
	s_mov_b32 s24, 0xfffffc0
	s_branch .LBB0_1292
